# MLA softmax with lazily-updated reference max folded into the QK MFMA C operand (no per-element subtract, rescale only when max grows by >8 in log2 units), MFMAs issued singly between VALU chunks
# speedup vs baseline: 1.0269x; 1.0269x over previous
; DI int tid_op() { int t = threadIdx.x & 255; asm volatile("" : "+v"(t)); return t; }
;     constexpr int KS = DQK + 8, NKS = DQK / 16, KCH = DQK / 8, NKL = 64 * KCH / 256;
;     const int tid = tid_op(), lane = tid & 63, w = tid >> 6, r = lane & 31, h = lane >> 5;
;     const int qidx = q0 + 32 * w + r;
;     bf16x8 qf[NKS];
; #pragma unroll
;     for (int s = 0; s < NKS; ++s) qf[s] = *(const bf16x8*)(Q + (size_t)(32 * w + r) * DQK + 16 * s + 8 * h);
;     float qn = 0.f;
;     if (MODE == 0 && DESC) {
; #pragma unroll
;         for (int s = 0; s < NKS; ++s)
; #pragma unroll
;             for (int j = 0; j < 8; ++j) { const float a = __uint_as_float(((unsigned)(unsigned short)qf[s][j]) << 16); qn += a * a; }
;         qn += xhalf_other(qn, h);
;         qn = sqrtf(qn) * kmax;
;     }
;     f32x16 o0, o1;
; #pragma unroll
;     for (int i = 0; i < 16; ++i) { o0[i] = 0.f; o1[i] = 0.f; }
;     float m = -INFINITY, lsum = 0.f, R = 1.f;
;     u32x4 rk[NKL], rv[2]; f32x4 rc = {0.f, 0.f, 0.f, 0.f};
;     const unsigned okk = (unsigned)(((tid / KCH) * DQK + (tid % KCH) * 8) * 2);
;     const unsigned ovv = (unsigned)(((tid >> 3) * ldv + (tid & 7) * 8) * 2), svv = (unsigned)(ldv * 64);
;     auto ld_tile = [&](int kt) {
;         const unsigned char* Kt = (const unsigned char*)(K + (size_t)(64 * kt) * DQK);
;         const unsigned char* Vt = (const unsigned char*)(VT + 64 * kt);
; #pragma unroll
;         for (int j = 0; j < NKL; ++j) rk[j] = *(const u32x4*)(Kt + (okk + j * 4096));
; #pragma unroll
;         for (int j = 0; j < 2; ++j) rv[j] = *(const u32x4*)(Vt + (ovv + j * svv));
;         if (cdec && tid < 16) rc = *(const f32x4*)(cdec + 64 * kt + 4 * tid);
;     };
;     auto st_tile = [&](int buf) {
;         bf16_t* sK = (bf16_t*)(smem + buf * ATT_BUF); bf16_t* sV = (bf16_t*)(smem + buf * ATT_BUF + 13312); float* sC = (float*)(smem + buf * ATT_BUF + 22528);
; #pragma unroll
;         for (int j = 0; j < NKL; ++j) { const int c = tid + 256 * j, row = c / KCH, kc = (c % KCH) * 8; *(u32x4*)(sK + row * KS + kc) = rk[j]; }
; #pragma unroll
;         for (int j = 0; j < 2; ++j) { const int c = tid + 256 * j, row = c >> 3, kc = (c & 7) * 8; *(u32x4*)(sV + row * LS + kc) = rv[j]; }
;         if (cdec && tid < 16) *(f32x4*)(sC + 4 * tid) = rc;
;     };
;     ld_tile(DESC ? ntiles - 1 : 0);
;     __syncthreads();
;     st_tile(0);
.LBB0_771:
	s_and_b64 vcc, exec, s[4:5]
	s_cbranch_vccz .LBB0_786
	s_lshl_b64 s[4:5], s[10:11], 13
	s_or_b32 s4, s4, s94
	s_mulk_i32 s5, 0xc0
	s_mul_hi_u32 s6, s4, 0xc0
	s_add_i32 s5, s6, s5
	s_mulk_i32 s4, 0xc0
	v_readlane_b32 s0, v254, 58
	s_add_u32 s6, s0, s4
	v_readlane_b32 s0, v254, 59
	v_mov_b32_e32 v8, v215
	s_addc_u32 s7, s0, s5
	s_mul_i32 s4, s10, 0x180000
	v_ashrrev_i32_e32 v9, 1, v8
	v_readlane_b32 s0, v254, 60
	v_bfe_u32 v121, v8, 5, 1
	v_bfi_b32 v110, s41, v9, v8
	v_mov_b64_e32 v[2:3], s[6:7]
	s_mul_hi_u32 s5, s10, 0x180000
	s_add_u32 s4, s0, s4
	v_readlane_b32 s0, v254, 61
	v_mad_i64_i32 v[2:3], s[6:7], v110, s85, v[2:3]
	v_lshlrev_b32_e32 v0, 4, v121
	s_addc_u32 s5, s0, s5
	v_lshl_add_u64 v[2:3], v[2:3], 0, v[0:1]
	v_lshlrev_b32_e32 v0, 4, v8
	v_lshl_add_u64 v[4:5], s[4:5], 0, v[0:1]
	v_add_u32_e32 v112, 0x1000, v0
	v_mov_b32_e32 v113, v1
	v_lshl_add_u64 v[6:7], s[4:5], 0, v[112:113]
	global_load_dwordx4 v[66:69], v[4:5], off
	global_load_dwordx4 v[70:73], v[6:7], off
	v_add_u32_e32 v114, 0x2000, v0
	v_mov_b32_e32 v115, v1
	s_lshl_b64 s[6:7], s[10:11], 20
	v_lshl_add_u64 v[4:5], s[4:5], 0, v[114:115]
	v_readlane_b32 s0, v254, 62
	global_load_dwordx4 v[74:77], v[4:5], off
	s_add_u32 s6, s0, s6
	v_readlane_b32 s0, v254, 63
	s_addc_u32 s7, s0, s7
	v_lshlrev_b32_e32 v4, 11, v8
	v_and_b32_e32 v5, 0x70, v0
	s_movk_i32 s0, 0xc000
	v_and_or_b32 v116, v4, s0, v5
	v_mov_b32_e32 v117, v1
	v_lshl_add_u64 v[4:5], s[6:7], 0, v[116:117]
	global_load_dwordx4 v[78:81], v[4:5], off
	v_add_u32_e32 v118, 0x80000, v116
	v_mov_b32_e32 v119, v1
	v_lshl_add_u64 v[4:5], s[6:7], 0, v[118:119]
	global_load_dwordx4 v[82:85], v[4:5], off
	global_load_dwordx4 v[86:89], v[2:3], off
	global_load_dwordx4 v[90:93], v[2:3], off offset:32
	global_load_dwordx4 v[94:97], v[2:3], off offset:64
	global_load_dwordx4 v[98:101], v[2:3], off offset:96
	global_load_dwordx4 v[102:105], v[2:3], off offset:128
	global_load_dwordx4 v[106:109], v[2:3], off offset:160
	s_add_u32 s14, s4, 0x3000
	s_addc_u32 s15, s5, 0
	global_load_dwordx4 v[176:179], v0, s[14:15]
	global_load_dwordx4 v[180:183], v112, s[14:15]
	global_load_dwordx4 v[184:187], v114, s[14:15]
	s_mov_b32 s0, 0x2aaaaaab
	v_mul_hi_i32 v5, v8, s0
	v_add_u32_e32 v6, 0x100, v8
	v_add_u32_e32 v7, 0x200, v8
	v_lshrrev_b32_e32 v11, 31, v5
	v_ashrrev_i32_e32 v5, 1, v5
	v_mul_hi_i32 v12, v6, s0
	v_and_b32_e32 v9, 0xffffffe0, v9
	v_mul_hi_i32 v13, v7, s0
	v_add_u32_e32 v2, v5, v11
	v_lshrrev_b32_e32 v3, 31, v12
	v_ashrrev_i32_e32 v5, 1, v12
	s_movk_i32 s0, 0x68
	v_add_u32_e32 v125, s94, v9
	v_lshrrev_b32_e32 v9, 31, v13
	v_ashrrev_i32_e32 v11, 1, v13
	v_mul_lo_u32 v12, v2, 12
	v_mul_lo_u32 v2, v2, s0
	v_add_u32_e32 v3, v5, v3
	v_add_u32_e32 v5, v11, v9
	v_sub_u32_e32 v9, v8, v12
	v_lshlrev_b32_e32 v127, 1, v2
	v_mul_lo_u32 v2, v3, 12
	v_mul_lo_u32 v3, v3, s0
	v_lshlrev_b32_e32 v11, 3, v9
	v_lshlrev_b32_e32 v9, 4, v9
	v_sub_u32_e32 v2, v6, v2
	v_lshlrev_b32_e32 v128, 1, v3
	v_add3_u32 v3, s33, v127, v9
	v_lshlrev_b32_e32 v9, 3, v2
	v_lshlrev_b32_e32 v2, 4, v2
	v_add3_u32 v2, s33, v128, v2
	s_waitcnt lgkmcnt(0)
	s_barrier
;     ...
;     f32x16 o0, o1;
; #pragma unroll
;     for (int i = 0; i < 16; ++i) { o0[i] = 0.f; o1[i] = 0.f; }
;     float m = -INFINITY, lsum = 0.f, R = 1.f;
;     u32x4 rk[NKL], rv[2]; f32x4 rc = {0.f, 0.f, 0.f, 0.f};
;     const unsigned okk = (unsigned)(((tid / KCH) * DQK + (tid % KCH) * 8) * 2);
;     const unsigned ovv = (unsigned)(((tid >> 3) * ldv + (tid & 7) * 8) * 2), svv = (unsigned)(ldv * 64);
;     auto ld_tile = [&](int kt) {
;         const unsigned char* Kt = (const unsigned char*)(K + (size_t)(64 * kt) * DQK);
;         const unsigned char* Vt = (const unsigned char*)(VT + 64 * kt);
; #pragma unroll
;         for (int j = 0; j < NKL; ++j) rk[j] = *(const u32x4*)(Kt + (okk + j * 4096));
; #pragma unroll
;         for (int j = 0; j < 2; ++j) rv[j] = *(const u32x4*)(Vt + (ovv + j * svv));
;         if (cdec && tid < 16) rc = *(const f32x4*)(cdec + 64 * kt + 4 * tid);
;     };
;     auto st_tile = [&](int buf) {
;         bf16_t* sK = (bf16_t*)(smem + buf * ATT_BUF); bf16_t* sV = (bf16_t*)(smem + buf * ATT_BUF + 13312); float* sC = (float*)(smem + buf * ATT_BUF + 22528);
; #pragma unroll
;         for (int j = 0; j < NKL; ++j) { const int c = tid + 256 * j, row = c / KCH, kc = (c % KCH) * 8; *(u32x4*)(sK + row * KS + kc) = rk[j]; }
; #pragma unroll
;         for (int j = 0; j < 2; ++j) { const int c = tid + 256 * j, row = c >> 3, kc = (c & 7) * 8; *(u32x4*)(sV + row * LS + kc) = rv[j]; }
;         if (cdec && tid < 16) *(f32x4*)(sC + 4 * tid) = rc;
;     };
;     ld_tile(DESC ? ntiles - 1 : 0);
;     __syncthreads();
;     st_tile(0);
; #pragma unroll 1
;     for (int it = 0; it < ntiles; ++it) {
;         const int kt = DESC ? ntiles - 1 - it : it, buf = it & 1;
;         if (it + 1 < ntiles) ld_tile(DESC ? kt - 1 : kt + 1);
;         __syncthreads();
;         if ((MODE == 1 || (MODE == 0 && DESC)) && it > 0) {
;             const int* fl = (const int*)(smem0 + SMEM_FLAG) + ((it - 1) & 1) * 8;
;             if ((fl[0] & fl[1] & fl[2] & fl[3] & fl[4] & fl[5] & fl[6] & fl[7]) != 0) break;
;         }
;         const bf16_t* sK = (const bf16_t*)(smem + buf * ATT_BUF); const bf16_t* sV = (const bf16_t*)(smem + buf * ATT_BUF + 13312);
;         const float* sC = (const float*)(smem + buf * ATT_BUF + 22528);
;         bool active = true;
;         if (MODE == 0) active = (64 * kt <= q0 + 32 * w + 31);
	v_and_b32_e32 v4, 31, v8
	v_lshlrev_b32_e32 v10, 3, v121
	s_waitcnt vmcnt(0)
	ds_write_b128 v3, v[66:69]
	ds_write_b128 v2, v[70:73]
	v_mul_lo_u32 v2, v5, 12
	v_sub_u32_e32 v2, v7, v2
	v_mul_lo_u32 v5, v5, s0
	v_lshlrev_b32_e32 v3, 3, v2
	v_lshlrev_b32_e32 v129, 1, v5
	v_lshlrev_b32_e32 v2, 4, v2
	v_add3_u32 v2, s33, v129, v2
	ds_write_b128 v2, v[74:77]
	v_lshrrev_b32_e32 v2, 3, v8
	v_lshlrev_b32_e32 v5, 3, v8
	s_movk_i32 s0, 0x48
	v_and_b32_e32 v5, 56, v5
	v_mul_lo_u32 v2, v2, s0
	v_lshlrev_b32_e32 v130, 1, v2
	v_lshlrev_b32_e32 v131, 1, v5
	v_and_b32_e32 v217, 1, v215
	v_lshlrev_b32_e32 v217, 3, v217
	v_sub_u32_e32 v217, v131, v217
	v_add_u32_e32 v217, 0x3400, v217
	v_add3_u32 v2, s33, v130, v217
	ds_write2_b64 v2, v[78:79], v[80:81] offset1:2
	v_lshrrev_b32_e32 v2, 3, v6
	v_mul_lo_u32 v2, v2, s0
	v_lshlrev_b32_e32 v132, 1, v2
	v_add3_u32 v2, s33, v132, v217
	v_mov_b32_e32 v18, v1
	v_mov_b32_e32 v19, v1
	v_or_b32_e32 v126, v125, v4
	ds_write2_b64 v2, v[82:83], v[84:85] offset1:2
	v_mul_u32_u24_e32 v134, 0xd0, v4
	v_mul_u32_u24_e32 v136, 0x90, v4
	v_mov_b32_e32 v20, v1
	v_mov_b32_e32 v21, v1
	v_mov_b32_e32 v22, v1
	v_mov_b32_e32 v23, v1
	v_mov_b32_e32 v24, v1
	v_mov_b32_e32 v25, v1
	v_mov_b32_e32 v26, v1
	v_mov_b32_e32 v27, v1
	v_mov_b32_e32 v28, v1
	v_mov_b32_e32 v29, v1
	v_mov_b32_e32 v30, v1
	v_mov_b32_e32 v31, v1
	v_mov_b32_e32 v32, v1
	v_mov_b32_e32 v33, v1
	v_lshlrev_b32_e32 v137, 1, v10
	v_lshlrev_b32_e32 v138, 1, v11
	v_lshlrev_b32_e32 v139, 1, v9
	v_lshlrev_b32_e32 v140, 1, v3
	v_mov_b64_e32 v[2:3], v[18:19]
	s_mov_b32 s95, s49
	v_ashrrev_i32_e32 v111, 31, v110
	v_or_b32_e32 v133, 31, v125
	v_lshlrev_b32_e32 v123, 2, v121
	s_mov_b32 s16, 0
	v_mov_b32_e32 v135, 0
	v_mov_b32_e32 v122, 0xff800000
	s_mov_b32 s12, 0
	v_mov_b64_e32 v[4:5], v[20:21]
	v_mov_b64_e32 v[6:7], v[22:23]
	v_mov_b64_e32 v[8:9], v[24:25]
	v_mov_b64_e32 v[10:11], v[26:27]
	v_mov_b64_e32 v[12:13], v[28:29]
	v_mov_b64_e32 v[14:15], v[30:31]
	v_mov_b64_e32 v[16:17], v[32:33]
	v_mov_b32_e32 v156, 0
	v_mov_b32_e32 v157, 0
	v_mov_b32_e32 v158, 0
	v_mov_b32_e32 v159, 0
	v_mov_b32_e32 v160, 0
	v_mov_b32_e32 v161, 0
	v_mov_b32_e32 v162, 0
	v_mov_b32_e32 v163, 0
	v_mov_b32_e32 v164, 0
	v_mov_b32_e32 v165, 0
	v_mov_b32_e32 v166, 0
	v_mov_b32_e32 v167, 0
	v_mov_b32_e32 v168, 0
	v_mov_b32_e32 v169, 0
	v_mov_b32_e32 v170, 0
	v_mov_b32_e32 v171, 0
	s_mov_b64 s[20:21], -1
	v_add3_u32 v127, s33, v127, v138
	v_add3_u32 v128, s33, v128, v139
	v_add3_u32 v129, s33, v129, v140
	v_add3_u32 v130, s33, v130, v217
	v_add3_u32 v132, s33, v132, v217
	v_add_u32_e32 v138, 0x5900, v130
	v_add_u32_e32 v139, 0x5900, v132
	v_add3_u32 v216, s33, v134, v137
	v_lshlrev_b32_e32 v231, 2, v123
	v_add3_u32 v231, s33, v136, v231
	ds_write_b128 v127, v[176:179] offset:22784
	ds_write_b128 v128, v[180:183] offset:22784
	ds_write_b128 v129, v[184:187] offset:22784
	s_waitcnt lgkmcnt(0)
	s_barrier
	ds_read_b128 v[208:211], v216 offset:0
	ds_read_b128 v[232:235], v216 offset:6656
	ds_read_b128 v[236:239], v216 offset:32
	ds_read_b128 v[240:243], v216 offset:6688
	ds_read_b128 v[244:247], v216 offset:64
	ds_read_b128 v[248:251], v216 offset:6720
	s_waitcnt lgkmcnt(4)
	v_mfma_f32_32x32x16_bf16 v[50:65], v[208:211], v[86:89], 0
	v_mfma_f32_32x32x16_bf16 v[34:49], v[232:235], v[86:89], 0
	ds_read_b128 v[208:211], v216 offset:96
	ds_read_b128 v[232:235], v216 offset:6752
	s_waitcnt lgkmcnt(4)
	v_mfma_f32_32x32x16_bf16 v[50:65], v[236:239], v[90:93], v[50:65]
	v_mfma_f32_32x32x16_bf16 v[34:49], v[240:243], v[90:93], v[34:49]
	ds_read_b128 v[236:239], v216 offset:128
	ds_read_b128 v[240:243], v216 offset:6784
	s_waitcnt lgkmcnt(4)
	v_mfma_f32_32x32x16_bf16 v[50:65], v[244:247], v[94:97], v[50:65]
	v_mfma_f32_32x32x16_bf16 v[34:49], v[248:251], v[94:97], v[34:49]
	ds_read_b128 v[244:247], v216 offset:160
	ds_read_b128 v[248:251], v216 offset:6816
	s_waitcnt lgkmcnt(4)
	v_mfma_f32_32x32x16_bf16 v[50:65], v[208:211], v[98:101], v[50:65]
	v_mfma_f32_32x32x16_bf16 v[34:49], v[232:235], v[98:101], v[34:49]
	s_waitcnt lgkmcnt(2)
	v_mfma_f32_32x32x16_bf16 v[50:65], v[236:239], v[102:105], v[50:65]
	v_mfma_f32_32x32x16_bf16 v[34:49], v[240:243], v[102:105], v[34:49]
	s_waitcnt lgkmcnt(0)
	v_mfma_f32_32x32x16_bf16 v[50:65], v[244:247], v[106:109], v[50:65]
	v_mfma_f32_32x32x16_bf16 v[34:49], v[248:251], v[106:109], v[34:49]
	s_nop 7
	s_nop 3

;     ...
;             for (int s = 0; s < NKS; ++s) {
;                 const bf16x8 k0 = *(const bf16x8*)(sK + r * KS + 16 * s + 8 * h), k1 = *(const bf16x8*)(sK + (32 + r) * KS + 16 * s + 8 * h);
;     ...
;                 float mx = fmaxf(s4[0][0].x, s4[1][0].x);
; #pragma unroll
;                 for (int qd = 0; qd < 4; ++qd) {
;                     mx = fmaxf(fmaxf(mx, s4[0][qd].y), s4[1][qd].y);
;                     mx = fmaxf(fmaxf(mx, s4[0][qd].z), s4[1][qd].z);
;                     mx = fmaxf(fmaxf(mx, s4[0][qd].w), s4[1][qd].w);
;                     if (qd < 3) mx = fmaxf(fmaxf(mx, s4[0][qd + 1].x), s4[1][qd + 1].x);
;                 }
;                 mx = xhalf_max(mx);
;                 const float mn = fmaxf(m, mx), alpha = fexp2(m - mn);
;                 m = mn;
;                 f32x4 ps4 = {0.f, 0.f, 0.f, 0.f};
;                 const float nmn = -mn;
;                 const f32x4 nm4 = {nmn, nmn, nmn, nmn};
;                 if (__builtin_amdgcn_ballot_w64(alpha != 1.f) != 0) { o0 *= alpha; o1 *= alpha; }
; #pragma unroll
;                 for (int s2 = 0; s2 < 4; ++s2) {
;                     const int mt = s2 >> 1, s = s2 & 1;
;                     f32x4 da = s4[mt][2 * s] + nm4, db = s4[mt][2 * s + 1] + nm4;
;                     da.x = fexp2(da.x); da.y = fexp2(da.y); da.z = fexp2(da.z); da.w = fexp2(da.w);
;                     db.x = fexp2(db.x); db.y = fexp2(db.y); db.z = fexp2(db.z); db.w = fexp2(db.w);
;                     ps4 += da; ps4 += db;
;                     u32x4 pp;
;                     pp.x = pk2(da.x, da.y); pp.y = pk2(da.z, da.w); pp.z = pk2(db.x, db.y); pp.w = pk2(db.z, db.w);
;                     const bf16x8 pfr = __builtin_bit_cast(bf16x8, pp);
;                     const s16x4 a0 = *(const s16x4*)(sV + r * LS + 16 * s2 + 4 * h), a1 = *(const s16x4*)(sV + r * LS + 16 * s2 + 8 + 4 * h);
;                     const s16x4 b0 = *(const s16x4*)(sV + (32 + r) * LS + 16 * s2 + 4 * h), b1 = *(const s16x4*)(sV + (32 + r) * LS + 16 * s2 + 8 + 4 * h);
;                     const bf16x8 v0 = __builtin_shufflevector(a0, a1, 0, 1, 2, 3, 4, 5, 6, 7), v1 = __builtin_shufflevector(b0, b1, 0, 1, 2, 3, 4, 5, 6, 7);
;                     o0 = MFMA32(v0, pfr, o0);
;                     o1 = MFMA32(v1, pfr, o1);
;                 }
;                 lsum = lsum * alpha + ((ps4.x + ps4.y) + (ps4.z + ps4.w));
.Lm3_nomask_e:
	s_or_b64 exec, exec, s[14:15]
	v_max3_f32 v120, v50, v51, v52
	v_max3_f32 v141, v53, v54, v55
	v_max3_f32 v154, v56, v57, v58
	v_max3_f32 v212, v59, v60, v61
	v_max3_f32 v120, v120, v62, v63
	v_max3_f32 v141, v141, v64, v65
	v_max3_f32 v154, v154, v34, v35
	v_max3_f32 v212, v212, v36, v37
	v_max3_f32 v120, v120, v38, v39
	v_max3_f32 v141, v141, v40, v41
	v_max3_f32 v154, v154, v42, v43
	v_max3_f32 v212, v212, v44, v45
	v_max3_f32 v120, v120, v46, v47
	v_max3_f32 v141, v141, v48, v49
	v_max3_f32 v120, v120, v141, v154
	v_max_f32_e32 v120, v120, v212
	v_mov_b32_e32 v141, v120
	s_nop 1
	v_permlane32_swap_b32_e32 v120, v141
	v_max_f32_e32 v120, v120, v141
	v_cmp_lt_f32_e32 vcc, 0x41000000, v120
	s_or_b64 vcc, vcc, s[20:21]
	s_cbranch_vccnz .Lm3_rare_e
.Lm3_back_e:
	s_waitcnt lgkmcnt(4)
	v_mfma_f32_32x32x16_bf16 v[176:191], v[208:211], v[86:89], v[156:171]
	v_exp_f32_e32 v50, v50
	v_exp_f32_e32 v51, v51
	v_exp_f32_e32 v52, v52
	v_mfma_f32_32x32x16_bf16 v[192:207], v[232:235], v[86:89], v[156:171]
	ds_read_b128 v[208:211], v216 offset:22880
	ds_read_b128 v[232:235], v216 offset:29536
	v_exp_f32_e32 v53, v53
	v_exp_f32_e32 v54, v54
	v_exp_f32_e32 v55, v55
	s_waitcnt lgkmcnt(4)
	v_mfma_f32_32x32x16_bf16 v[176:191], v[236:239], v[90:93], v[176:191]
	v_exp_f32_e32 v56, v56
	v_exp_f32_e32 v57, v57
	v_cvt_pk_bf16_f32 v142, v50, v51
	v_mfma_f32_32x32x16_bf16 v[192:207], v[240:243], v[90:93], v[192:207]
	ds_read_b128 v[236:239], v231 offset:13312
	ds_read_b128 v[240:243], v231 offset:17920
	v_cvt_pk_bf16_f32 v143, v52, v53
	v_cvt_pk_bf16_f32 v144, v54, v55
	v_cvt_pk_bf16_f32 v145, v56, v57
	v_exp_f32_e32 v58, v58
	s_waitcnt lgkmcnt(4)
	v_mfma_f32_32x32x16_bf16 v[176:191], v[244:247], v[94:97], v[176:191]
	v_exp_f32_e32 v59, v59
	v_exp_f32_e32 v60, v60
	v_exp_f32_e32 v61, v61
	v_mfma_f32_32x32x16_bf16 v[192:207], v[248:251], v[94:97], v[192:207]
	ds_read_b128 v[244:247], v216 offset:22912
	ds_read_b128 v[248:251], v216 offset:29568
	v_exp_f32_e32 v62, v62
	v_exp_f32_e32 v63, v63
	v_exp_f32_e32 v64, v64
	s_waitcnt lgkmcnt(4)
	v_mfma_f32_32x32x16_bf16 v[176:191], v[208:211], v[98:101], v[176:191]
	v_exp_f32_e32 v65, v65
	v_cvt_pk_bf16_f32 v146, v58, v59
	v_cvt_pk_bf16_f32 v147, v60, v61
	v_cvt_pk_bf16_f32 v148, v62, v63
	v_mfma_f32_32x32x16_bf16 v[192:207], v[232:235], v[98:101], v[192:207]
	ds_read_b128 v[208:211], v231 offset:13344
	ds_read_b128 v[232:235], v231 offset:17952
	v_cvt_pk_bf16_f32 v149, v64, v65
	v_exp_f32_e32 v34, v34
	v_exp_f32_e32 v35, v35
	s_waitcnt lgkmcnt(4)
	v_mfma_f32_32x32x16_bf16 v[18:33], v[236:239], v[142:145], v[18:33]
	v_exp_f32_e32 v36, v36
	v_exp_f32_e32 v37, v37
	v_exp_f32_e32 v38, v38
	v_mfma_f32_32x32x16_bf16 v[2:17], v[240:243], v[142:145], v[2:17]
	ds_read_b128 v[236:239], v216 offset:22944
	ds_read_b128 v[240:243], v216 offset:29600
	v_exp_f32_e32 v39, v39
	v_exp_f32_e32 v40, v40
	v_exp_f32_e32 v41, v41
	s_waitcnt lgkmcnt(4)
	v_mfma_f32_32x32x16_bf16 v[176:191], v[244:247], v[102:105], v[176:191]
	v_cvt_pk_bf16_f32 v150, v34, v35
	v_cvt_pk_bf16_f32 v151, v36, v37
	v_cvt_pk_bf16_f32 v152, v38, v39
	v_cvt_pk_bf16_f32 v153, v40, v41
	v_exp_f32_e32 v42, v42
	v_mfma_f32_32x32x16_bf16 v[192:207], v[248:251], v[102:105], v[192:207]
	ds_read_b128 v[244:247], v231 offset:13376
	ds_read_b128 v[248:251], v231 offset:17984
	v_exp_f32_e32 v43, v43
	v_exp_f32_e32 v44, v44
	v_exp_f32_e32 v45, v45
	s_waitcnt lgkmcnt(4)
	v_mfma_f32_32x32x16_bf16 v[18:33], v[208:211], v[146:149], v[18:33]
	v_exp_f32_e32 v46, v46
	v_exp_f32_e32 v47, v47
	v_mfma_f32_32x32x16_bf16 v[2:17], v[232:235], v[146:149], v[2:17]
	ds_read_b128 v[208:211], v231 offset:13408
	ds_read_b128 v[232:235], v231 offset:18016
	v_exp_f32_e32 v48, v48
	v_exp_f32_e32 v49, v49
	v_cvt_pk_bf16_f32 v142, v42, v43
	v_cvt_pk_bf16_f32 v143, v44, v45
	s_waitcnt lgkmcnt(4)
	v_mfma_f32_32x32x16_bf16 v[176:191], v[236:239], v[106:109], v[176:191]
	v_cvt_pk_bf16_f32 v144, v46, v47
	v_cvt_pk_bf16_f32 v145, v48, v49
	v_add_f32_e32 v141, v50, v51
	v_add_f32_e32 v154, v52, v53
	v_add_f32_e32 v212, v54, v55
	v_add_f32_e32 v213, v56, v57
	v_mfma_f32_32x32x16_bf16 v[192:207], v[240:243], v[106:109], v[192:207]
	v_add_f32_e32 v141, v141, v154
	v_add_f32_e32 v212, v212, v213
	v_add_f32_e32 v230, v141, v212
	v_add_f32_e32 v141, v58, v59
	v_add_f32_e32 v154, v60, v61
	v_add_f32_e32 v212, v62, v63
	s_waitcnt lgkmcnt(2)
	v_mfma_f32_32x32x16_bf16 v[18:33], v[244:247], v[150:153], v[18:33]
	v_add_f32_e32 v213, v64, v65
	v_add_f32_e32 v141, v141, v154
	v_add_f32_e32 v212, v212, v213
	v_add_f32_e32 v141, v141, v212
	v_add_f32_e32 v230, v230, v141
	v_mfma_f32_32x32x16_bf16 v[2:17], v[248:251], v[150:153], v[2:17]
	v_add_f32_e32 v141, v34, v35
	v_add_f32_e32 v154, v36, v37
	v_add_f32_e32 v212, v38, v39
	v_add_f32_e32 v213, v40, v41
	v_add_f32_e32 v141, v141, v154
	v_add_f32_e32 v212, v212, v213
	s_waitcnt lgkmcnt(0)
	v_mfma_f32_32x32x16_bf16 v[18:33], v[208:211], v[142:145], v[18:33]
	v_add_f32_e32 v141, v141, v212
	v_add_f32_e32 v230, v230, v141
	v_add_f32_e32 v141, v42, v43
	v_add_f32_e32 v154, v44, v45
	v_add_f32_e32 v212, v46, v47
	v_mfma_f32_32x32x16_bf16 v[2:17], v[232:235], v[142:145], v[2:17]
	v_add_f32_e32 v213, v48, v49
	v_add_f32_e32 v141, v141, v154
	v_add_f32_e32 v212, v212, v213
	v_add_f32_e32 v141, v141, v212
	v_add_f32_e32 v230, v230, v141
	v_add_f32_e32 v135, v135, v230
	s_waitcnt vmcnt(0)
	ds_write2_b64 v138, v[78:79], v[80:81] offset1:2
	ds_write2_b64 v139, v[82:83], v[84:85] offset1:2
	s_cmp_ge_u32 s17, s66
	s_cbranch_scc1 .Lm3_even_nokw
	ds_write_b128 v127, v[66:69]
	ds_write_b128 v128, v[70:73]
	ds_write_b128 v129, v[74:77]
;     ...
;     auto ld_tile = [&](int kt) {
;         const unsigned char* Kt = (const unsigned char*)(K + (size_t)(64 * kt) * DQK);
;         const unsigned char* Vt = (const unsigned char*)(VT + 64 * kt);
; #pragma unroll
;     ...
;                 float mx = fmaxf(s4[0][0].x, s4[1][0].x);
; #pragma unroll
;                 for (int qd = 0; qd < 4; ++qd) {
;                     mx = fmaxf(fmaxf(mx, s4[0][qd].y), s4[1][qd].y);
;                     mx = fmaxf(fmaxf(mx, s4[0][qd].z), s4[1][qd].z);
;                     mx = fmaxf(fmaxf(mx, s4[0][qd].w), s4[1][qd].w);
;                     if (qd < 3) mx = fmaxf(fmaxf(mx, s4[0][qd + 1].x), s4[1][qd + 1].x);
;                 }
;                 mx = xhalf_max(mx);
;                 const float mn = fmaxf(m, mx), alpha = fexp2(m - mn);
;                 m = mn;
;                 f32x4 ps4 = {0.f, 0.f, 0.f, 0.f};
;                 const float nmn = -mn;
;                 const f32x4 nm4 = {nmn, nmn, nmn, nmn};
;                 if (__builtin_amdgcn_ballot_w64(alpha != 1.f) != 0) { o0 *= alpha; o1 *= alpha; }
; #pragma unroll
;                 for (int s2 = 0; s2 < 4; ++s2) {
;                     const int mt = s2 >> 1, s = s2 & 1;
;                     f32x4 da = s4[mt][2 * s] + nm4, db = s4[mt][2 * s + 1] + nm4;
;                     da.x = fexp2(da.x); da.y = fexp2(da.y); da.z = fexp2(da.z); da.w = fexp2(da.w);
;                     db.x = fexp2(db.x); db.y = fexp2(db.y); db.z = fexp2(db.z); db.w = fexp2(db.w);
;                     ps4 += da; ps4 += db;
;                     u32x4 pp;
;                     pp.x = pk2(da.x, da.y); pp.y = pk2(da.z, da.w); pp.z = pk2(db.x, db.y); pp.w = pk2(db.z, db.w);
;                     const bf16x8 pfr = __builtin_bit_cast(bf16x8, pp);
;                     const s16x4 a0 = *(const s16x4*)(sV + r * LS + 16 * s2 + 4 * h), a1 = *(const s16x4*)(sV + r * LS + 16 * s2 + 8 + 4 * h);
;                     const s16x4 b0 = *(const s16x4*)(sV + (32 + r) * LS + 16 * s2 + 4 * h), b1 = *(const s16x4*)(sV + (32 + r) * LS + 16 * s2 + 8 + 4 * h);
;                     const bf16x8 v0 = __builtin_shufflevector(a0, a1, 0, 1, 2, 3, 4, 5, 6, 7), v1 = __builtin_shufflevector(b0, b1, 0, 1, 2, 3, 4, 5, 6, 7);
;                     o0 = MFMA32(v0, pfr, o0);
;                     o1 = MFMA32(v1, pfr, o1);
;                 }
;                 lsum = lsum * alpha + ((ps4.x + ps4.y) + (ps4.z + ps4.w));
.Lm3_even_nokw:
	s_add_i32 s12, s12, 1
	s_add_i32 s16, s16, 64
	s_add_i32 s17, s12, 1
	s_cmp_ge_u32 s17, s66
	s_cbranch_scc1 .Lm3_final
	s_add_i32 s48, s16, 64
	s_lshl_b64 s[14:15], s[48:49], 1
	s_add_u32 s14, s6, s14
	s_addc_u32 s15, s7, s15
	global_load_dwordx4 v[78:81], v116, s[14:15]
	global_load_dwordx4 v[82:85], v118, s[14:15]
	s_add_i32 s48, s16, 0x80
	s_mul_i32 s14, s48, 0xc0
	s_mul_hi_u32 s13, s48, 0xc0
	s_add_u32 s14, s4, s14
	s_addc_u32 s15, s5, s13
	global_load_dwordx4 v[66:69], v0, s[14:15]
	global_load_dwordx4 v[70:73], v112, s[14:15]
	global_load_dwordx4 v[74:77], v114, s[14:15]
	s_waitcnt lgkmcnt(0)
	s_barrier
	ds_read_b128 v[208:211], v216 offset:0
	ds_read_b128 v[232:235], v216 offset:6656
	ds_read_b128 v[236:239], v216 offset:32
	ds_read_b128 v[240:243], v216 offset:6688
	ds_read_b128 v[244:247], v216 offset:64
	ds_read_b128 v[248:251], v216 offset:6720
	v_max3_f32 v120, v176, v177, v178
	v_max3_f32 v141, v179, v180, v181
	v_max3_f32 v154, v182, v183, v184
	v_max3_f32 v212, v185, v186, v187
	v_max3_f32 v120, v120, v188, v189
	v_max3_f32 v141, v141, v190, v191
	v_max3_f32 v154, v154, v192, v193
	v_max3_f32 v212, v212, v194, v195
	v_max3_f32 v120, v120, v196, v197
	v_max3_f32 v141, v141, v198, v199
	v_max3_f32 v154, v154, v200, v201
	v_max3_f32 v212, v212, v202, v203
	v_max3_f32 v120, v120, v204, v205
	v_max3_f32 v141, v141, v206, v207
	v_max3_f32 v120, v120, v141, v154
	v_max_f32_e32 v120, v120, v212
	v_mov_b32_e32 v141, v120
	s_nop 1
	v_permlane32_swap_b32_e32 v120, v141
	v_max_f32_e32 v120, v120, v141
	v_cmp_lt_f32_e32 vcc, 0x41000000, v120
	s_or_b64 vcc, vcc, s[20:21]
	s_cbranch_vccnz .Lm3_rare_o
.Lm3_back_o:
	s_waitcnt lgkmcnt(4)
	v_mfma_f32_32x32x16_bf16 v[50:65], v[208:211], v[86:89], v[156:171]
	v_exp_f32_e32 v176, v176
	v_exp_f32_e32 v177, v177
	v_exp_f32_e32 v178, v178
	v_mfma_f32_32x32x16_bf16 v[34:49], v[232:235], v[86:89], v[156:171]
	ds_read_b128 v[208:211], v216 offset:96
	ds_read_b128 v[232:235], v216 offset:6752
	v_exp_f32_e32 v179, v179
	v_exp_f32_e32 v180, v180
	v_exp_f32_e32 v181, v181
	s_waitcnt lgkmcnt(4)
	v_mfma_f32_32x32x16_bf16 v[50:65], v[236:239], v[90:93], v[50:65]
	v_exp_f32_e32 v182, v182
	v_exp_f32_e32 v183, v183
	v_cvt_pk_bf16_f32 v142, v176, v177
	v_mfma_f32_32x32x16_bf16 v[34:49], v[240:243], v[90:93], v[34:49]
	ds_read_b128 v[236:239], v231 offset:36096
	ds_read_b128 v[240:243], v231 offset:40704
	v_cvt_pk_bf16_f32 v143, v178, v179
	v_cvt_pk_bf16_f32 v144, v180, v181
	v_cvt_pk_bf16_f32 v145, v182, v183
	v_exp_f32_e32 v184, v184
	s_waitcnt lgkmcnt(4)
	v_mfma_f32_32x32x16_bf16 v[50:65], v[244:247], v[94:97], v[50:65]
	v_exp_f32_e32 v185, v185
	v_exp_f32_e32 v186, v186
	v_exp_f32_e32 v187, v187
	v_mfma_f32_32x32x16_bf16 v[34:49], v[248:251], v[94:97], v[34:49]
	ds_read_b128 v[244:247], v216 offset:128
	ds_read_b128 v[248:251], v216 offset:6784
	v_exp_f32_e32 v188, v188
	v_exp_f32_e32 v189, v189
	v_exp_f32_e32 v190, v190
	s_waitcnt lgkmcnt(4)
	v_mfma_f32_32x32x16_bf16 v[50:65], v[208:211], v[98:101], v[50:65]
	v_exp_f32_e32 v191, v191
	v_cvt_pk_bf16_f32 v146, v184, v185
	v_cvt_pk_bf16_f32 v147, v186, v187
	v_cvt_pk_bf16_f32 v148, v188, v189
	v_mfma_f32_32x32x16_bf16 v[34:49], v[232:235], v[98:101], v[34:49]
	ds_read_b128 v[208:211], v231 offset:36128
	ds_read_b128 v[232:235], v231 offset:40736
	v_cvt_pk_bf16_f32 v149, v190, v191
	v_exp_f32_e32 v192, v192
	v_exp_f32_e32 v193, v193
	s_waitcnt lgkmcnt(4)
	v_mfma_f32_32x32x16_bf16 v[18:33], v[236:239], v[142:145], v[18:33]
	v_exp_f32_e32 v194, v194
	v_exp_f32_e32 v195, v195
	v_exp_f32_e32 v196, v196
	v_mfma_f32_32x32x16_bf16 v[2:17], v[240:243], v[142:145], v[2:17]
	ds_read_b128 v[236:239], v216 offset:160
	ds_read_b128 v[240:243], v216 offset:6816
	v_exp_f32_e32 v197, v197
	v_exp_f32_e32 v198, v198
	v_exp_f32_e32 v199, v199
	s_waitcnt lgkmcnt(4)
	v_mfma_f32_32x32x16_bf16 v[50:65], v[244:247], v[102:105], v[50:65]
	v_cvt_pk_bf16_f32 v150, v192, v193
	v_cvt_pk_bf16_f32 v151, v194, v195
	v_cvt_pk_bf16_f32 v152, v196, v197
	v_cvt_pk_bf16_f32 v153, v198, v199
	v_exp_f32_e32 v200, v200
	v_mfma_f32_32x32x16_bf16 v[34:49], v[248:251], v[102:105], v[34:49]
	ds_read_b128 v[244:247], v231 offset:36160
	ds_read_b128 v[248:251], v231 offset:40768
	v_exp_f32_e32 v201, v201
	v_exp_f32_e32 v202, v202
	v_exp_f32_e32 v203, v203
	s_waitcnt lgkmcnt(4)
	v_mfma_f32_32x32x16_bf16 v[18:33], v[208:211], v[146:149], v[18:33]
	v_exp_f32_e32 v204, v204
	v_exp_f32_e32 v205, v205
	v_mfma_f32_32x32x16_bf16 v[2:17], v[232:235], v[146:149], v[2:17]
	ds_read_b128 v[208:211], v231 offset:36192
	ds_read_b128 v[232:235], v231 offset:40800
	v_exp_f32_e32 v206, v206
	v_exp_f32_e32 v207, v207
	v_cvt_pk_bf16_f32 v142, v200, v201
	v_cvt_pk_bf16_f32 v143, v202, v203
	s_waitcnt lgkmcnt(4)
	v_mfma_f32_32x32x16_bf16 v[50:65], v[236:239], v[106:109], v[50:65]
	v_cvt_pk_bf16_f32 v144, v204, v205
	v_cvt_pk_bf16_f32 v145, v206, v207
	v_add_f32_e32 v141, v176, v177
	v_add_f32_e32 v154, v178, v179
	v_add_f32_e32 v212, v180, v181
	v_add_f32_e32 v213, v182, v183
	v_mfma_f32_32x32x16_bf16 v[34:49], v[240:243], v[106:109], v[34:49]
	v_add_f32_e32 v141, v141, v154
	v_add_f32_e32 v212, v212, v213
	v_add_f32_e32 v230, v141, v212
	v_add_f32_e32 v141, v184, v185
	v_add_f32_e32 v154, v186, v187
	v_add_f32_e32 v212, v188, v189
	s_waitcnt lgkmcnt(2)
	v_mfma_f32_32x32x16_bf16 v[18:33], v[244:247], v[150:153], v[18:33]
	v_add_f32_e32 v213, v190, v191
	v_add_f32_e32 v141, v141, v154
	v_add_f32_e32 v212, v212, v213
	v_add_f32_e32 v141, v141, v212
	v_add_f32_e32 v230, v230, v141
	v_mfma_f32_32x32x16_bf16 v[2:17], v[248:251], v[150:153], v[2:17]
	v_add_f32_e32 v141, v192, v193
	v_add_f32_e32 v154, v194, v195
	v_add_f32_e32 v212, v196, v197
	v_add_f32_e32 v213, v198, v199
	v_add_f32_e32 v141, v141, v154
	v_add_f32_e32 v212, v212, v213
	s_waitcnt lgkmcnt(0)
	v_mfma_f32_32x32x16_bf16 v[18:33], v[208:211], v[142:145], v[18:33]
	v_add_f32_e32 v141, v141, v212
	v_add_f32_e32 v230, v230, v141
	v_add_f32_e32 v141, v200, v201
	v_add_f32_e32 v154, v202, v203
	v_add_f32_e32 v212, v204, v205
	v_mfma_f32_32x32x16_bf16 v[2:17], v[232:235], v[142:145], v[2:17]
	v_add_f32_e32 v213, v206, v207
	v_add_f32_e32 v141, v141, v154
	v_add_f32_e32 v212, v212, v213
	v_add_f32_e32 v141, v141, v212
	v_add_f32_e32 v230, v230, v141
	v_add_f32_e32 v135, v135, v230
	s_waitcnt vmcnt(0)
	ds_write2_b64 v130, v[78:79], v[80:81] offset1:2
	ds_write2_b64 v132, v[82:83], v[84:85] offset1:2
	ds_write_b128 v127, v[66:69] offset:22784
	ds_write_b128 v128, v[70:73] offset:22784
	ds_write_b128 v129, v[74:77] offset:22784
	s_add_i32 s12, s12, 1
	s_add_i32 s16, s16, 64
	s_branch .Lm3_even

; DI unsigned pk2(float a, float b) { f32x2 v = {a, b}; return __builtin_bit_cast(unsigned, __builtin_convertvector(v, bf2_t)); }
; #define MFMA32(a, b, c) __builtin_amdgcn_mfma_f32_32x32x16_bf16((a), (b), (c), 0, 0, 0)
;     ...
;                 float mx = fmaxf(s4[0][0].x, s4[1][0].x);
; #pragma unroll
;                 for (int qd = 0; qd < 4; ++qd) {
;                     mx = fmaxf(fmaxf(mx, s4[0][qd].y), s4[1][qd].y);
;                     mx = fmaxf(fmaxf(mx, s4[0][qd].z), s4[1][qd].z);
;                     mx = fmaxf(fmaxf(mx, s4[0][qd].w), s4[1][qd].w);
;                     if (qd < 3) mx = fmaxf(fmaxf(mx, s4[0][qd + 1].x), s4[1][qd + 1].x);
;                 }
;                 mx = xhalf_max(mx);
;                 const float mn = fmaxf(m, mx), alpha = fexp2(m - mn);
;                 m = mn;
;                 f32x4 ps4 = {0.f, 0.f, 0.f, 0.f};
;                 const float nmn = -mn;
;                 const f32x4 nm4 = {nmn, nmn, nmn, nmn};
;                 if (__builtin_amdgcn_ballot_w64(alpha != 1.f) != 0) { o0 *= alpha; o1 *= alpha; }
; #pragma unroll
;                 for (int s2 = 0; s2 < 4; ++s2) {
;                     const int mt = s2 >> 1, s = s2 & 1;
;                     f32x4 da = s4[mt][2 * s] + nm4, db = s4[mt][2 * s + 1] + nm4;
;                     da.x = fexp2(da.x); da.y = fexp2(da.y); da.z = fexp2(da.z); da.w = fexp2(da.w);
;                     db.x = fexp2(db.x); db.y = fexp2(db.y); db.z = fexp2(db.z); db.w = fexp2(db.w);
;                     ps4 += da; ps4 += db;
;                     u32x4 pp;
;                     pp.x = pk2(da.x, da.y); pp.y = pk2(da.z, da.w); pp.z = pk2(db.x, db.y); pp.w = pk2(db.z, db.w);
;                     const bf16x8 pfr = __builtin_bit_cast(bf16x8, pp);
;                     const s16x4 a0 = *(const s16x4*)(sV + r * LS + 16 * s2 + 4 * h), a1 = *(const s16x4*)(sV + r * LS + 16 * s2 + 8 + 4 * h);
;                     const s16x4 b0 = *(const s16x4*)(sV + (32 + r) * LS + 16 * s2 + 4 * h), b1 = *(const s16x4*)(sV + (32 + r) * LS + 16 * s2 + 8 + 4 * h);
;                     const bf16x8 v0 = __builtin_shufflevector(a0, a1, 0, 1, 2, 3, 4, 5, 6, 7), v1 = __builtin_shufflevector(b0, b1, 0, 1, 2, 3, 4, 5, 6, 7);
;                     o0 = MFMA32(v0, pfr, o0);
;                     o1 = MFMA32(v1, pfr, o1);
;                 }
;                 lsum = lsum * alpha + ((ps4.x + ps4.y) + (ps4.z + ps4.w));
.Lm3_nomask_f:
	s_or_b64 exec, exec, s[14:15]
	v_max3_f32 v120, v176, v177, v178
	v_max3_f32 v141, v179, v180, v181
	v_max3_f32 v154, v182, v183, v184
	v_max3_f32 v212, v185, v186, v187
	v_max3_f32 v120, v120, v188, v189
	v_max3_f32 v141, v141, v190, v191
	v_max3_f32 v154, v154, v192, v193
	v_max3_f32 v212, v212, v194, v195
	v_max3_f32 v120, v120, v196, v197
	v_max3_f32 v141, v141, v198, v199
	v_max3_f32 v154, v154, v200, v201
	v_max3_f32 v212, v212, v202, v203
	v_max3_f32 v120, v120, v204, v205
	v_max3_f32 v141, v141, v206, v207
	v_max3_f32 v120, v120, v141, v154
	v_max_f32_e32 v120, v120, v212
	v_mov_b32_e32 v141, v120
	s_nop 1
	v_permlane32_swap_b32_e32 v120, v141
	v_max_f32_e32 v120, v120, v141
	v_cmp_lt_f32_e32 vcc, 0x41000000, v120
	s_or_b64 vcc, vcc, s[20:21]
	s_cbranch_vccnz .Lm3_rare_f
.Lm3_back_f:
	v_exp_f32_e32 v176, v176
	v_exp_f32_e32 v177, v177
	v_exp_f32_e32 v178, v178
	v_exp_f32_e32 v179, v179
	v_exp_f32_e32 v180, v180
	v_exp_f32_e32 v181, v181
	v_exp_f32_e32 v182, v182
	v_exp_f32_e32 v183, v183
	v_cvt_pk_bf16_f32 v142, v176, v177
	v_cvt_pk_bf16_f32 v143, v178, v179
	v_cvt_pk_bf16_f32 v144, v180, v181
	v_cvt_pk_bf16_f32 v145, v182, v183
	v_exp_f32_e32 v184, v184
	v_exp_f32_e32 v185, v185
	v_exp_f32_e32 v186, v186
	v_exp_f32_e32 v187, v187
	s_waitcnt lgkmcnt(4)
	v_mfma_f32_32x32x16_bf16 v[18:33], v[208:211], v[142:145], v[18:33]
	v_mfma_f32_32x32x16_bf16 v[2:17], v[232:235], v[142:145], v[2:17]
	ds_read_b128 v[208:211], v231 offset:36192
	ds_read_b128 v[232:235], v231 offset:40800
	v_exp_f32_e32 v188, v188
	v_exp_f32_e32 v189, v189
	v_exp_f32_e32 v190, v190
	v_exp_f32_e32 v191, v191
	v_add_f32_e32 v141, v176, v177
	v_add_f32_e32 v154, v178, v179
	v_add_f32_e32 v212, v180, v181
	v_add_f32_e32 v213, v182, v183
	v_add_f32_e32 v141, v141, v154
	v_add_f32_e32 v212, v212, v213
	v_add_f32_e32 v230, v141, v212
	v_cvt_pk_bf16_f32 v146, v184, v185
	v_cvt_pk_bf16_f32 v147, v186, v187
	v_cvt_pk_bf16_f32 v148, v188, v189
	v_cvt_pk_bf16_f32 v149, v190, v191
	v_exp_f32_e32 v192, v192
	v_exp_f32_e32 v193, v193
	v_exp_f32_e32 v194, v194
	v_exp_f32_e32 v195, v195
	s_waitcnt lgkmcnt(4)
	v_mfma_f32_32x32x16_bf16 v[18:33], v[236:239], v[146:149], v[18:33]
	v_mfma_f32_32x32x16_bf16 v[2:17], v[240:243], v[146:149], v[2:17]
	v_exp_f32_e32 v196, v196
	v_exp_f32_e32 v197, v197
	v_exp_f32_e32 v198, v198
	v_exp_f32_e32 v199, v199
	v_add_f32_e32 v141, v184, v185
	v_add_f32_e32 v154, v186, v187
	v_add_f32_e32 v212, v188, v189
	v_add_f32_e32 v213, v190, v191
	v_add_f32_e32 v141, v141, v154
	v_add_f32_e32 v212, v212, v213
	v_add_f32_e32 v141, v141, v212
	v_add_f32_e32 v230, v230, v141
	v_cvt_pk_bf16_f32 v150, v192, v193
	v_cvt_pk_bf16_f32 v151, v194, v195
	v_cvt_pk_bf16_f32 v152, v196, v197
	v_cvt_pk_bf16_f32 v153, v198, v199
	v_exp_f32_e32 v200, v200
	v_exp_f32_e32 v201, v201
	v_exp_f32_e32 v202, v202
	v_exp_f32_e32 v203, v203
	s_waitcnt lgkmcnt(2)
	v_mfma_f32_32x32x16_bf16 v[18:33], v[244:247], v[150:153], v[18:33]
	v_mfma_f32_32x32x16_bf16 v[2:17], v[248:251], v[150:153], v[2:17]
	v_exp_f32_e32 v204, v204
	v_exp_f32_e32 v205, v205
	v_exp_f32_e32 v206, v206
	v_exp_f32_e32 v207, v207
	v_add_f32_e32 v141, v192, v193
	v_add_f32_e32 v154, v194, v195
	v_add_f32_e32 v212, v196, v197
	v_add_f32_e32 v213, v198, v199
	v_add_f32_e32 v141, v141, v154
	v_add_f32_e32 v212, v212, v213
	v_add_f32_e32 v141, v141, v212
	v_add_f32_e32 v230, v230, v141
	v_cvt_pk_bf16_f32 v142, v200, v201
	v_cvt_pk_bf16_f32 v143, v202, v203
	v_cvt_pk_bf16_f32 v144, v204, v205
	v_cvt_pk_bf16_f32 v145, v206, v207
	v_add_f32_e32 v141, v200, v201
	v_add_f32_e32 v154, v202, v203
	v_add_f32_e32 v212, v204, v205
	v_add_f32_e32 v213, v206, v207
	s_waitcnt lgkmcnt(0)
	v_mfma_f32_32x32x16_bf16 v[18:33], v[208:211], v[142:145], v[18:33]
	v_mfma_f32_32x32x16_bf16 v[2:17], v[232:235], v[142:145], v[2:17]
	v_add_f32_e32 v141, v141, v154
	v_add_f32_e32 v212, v212, v213
	v_add_f32_e32 v141, v141, v212
	v_add_f32_e32 v230, v230, v141
	v_add_f32_e32 v135, v135, v230
.Lm3_done:
	s_or_b64 exec, exec, s[12:13]
	s_branch .Lm3_exit
; DI float xhalf_max(float x) { auto r = __builtin_amdgcn_permlane32_swap(__float_as_uint(x), __float_as_uint(x), false, false); return fmaxf(__uint_as_float(r[0]), __uint_as_float(r[1])); }
; DI float fexp2(float x) { return __builtin_amdgcn_exp2f(x); }
;     ...
;                 mx = xhalf_max(mx);
;                 const float mn = fmaxf(m, mx), alpha = fexp2(m - mn);
;                 m = mn;
;                 f32x4 ps4 = {0.f, 0.f, 0.f, 0.f};
;                 const float nmn = -mn;
;                 const f32x4 nm4 = {nmn, nmn, nmn, nmn};
;                 if (__builtin_amdgcn_ballot_w64(alpha != 1.f) != 0) { o0 *= alpha; o1 *= alpha; }
.Lm3_rare_e:
	s_nop 1
	v_cndmask_b32_e64 v122, 0, v120, vcc
	s_mov_b64 s[20:21], 0
	v_sub_f32_e32 v156, v156, v122
	v_sub_f32_e32 v157, v157, v122
	v_sub_f32_e32 v158, v158, v122
	v_sub_f32_e32 v159, v159, v122
	v_sub_f32_e32 v160, v160, v122
	v_sub_f32_e32 v161, v161, v122
	v_sub_f32_e32 v162, v162, v122
	v_sub_f32_e32 v163, v163, v122
	v_sub_f32_e32 v164, v164, v122
	v_sub_f32_e32 v165, v165, v122
	v_sub_f32_e32 v166, v166, v122
	v_sub_f32_e32 v167, v167, v122
	v_sub_f32_e32 v168, v168, v122
	v_sub_f32_e32 v169, v169, v122
	v_sub_f32_e32 v170, v170, v122
	v_sub_f32_e32 v171, v171, v122
	v_sub_f32_e32 v50, v50, v122
	v_sub_f32_e32 v51, v51, v122
	v_sub_f32_e32 v52, v52, v122
	v_sub_f32_e32 v53, v53, v122
	v_sub_f32_e32 v54, v54, v122
	v_sub_f32_e32 v55, v55, v122
	v_sub_f32_e32 v56, v56, v122
	v_sub_f32_e32 v57, v57, v122
	v_sub_f32_e32 v58, v58, v122
	v_sub_f32_e32 v59, v59, v122
	v_sub_f32_e32 v60, v60, v122
	v_sub_f32_e32 v61, v61, v122
	v_sub_f32_e32 v62, v62, v122
	v_sub_f32_e32 v63, v63, v122
	v_sub_f32_e32 v64, v64, v122
	v_sub_f32_e32 v65, v65, v122
	v_sub_f32_e32 v34, v34, v122
	v_sub_f32_e32 v35, v35, v122
	v_sub_f32_e32 v36, v36, v122
	v_sub_f32_e32 v37, v37, v122
	v_sub_f32_e32 v38, v38, v122
	v_sub_f32_e32 v39, v39, v122
	v_sub_f32_e32 v40, v40, v122
	v_sub_f32_e32 v41, v41, v122
	v_sub_f32_e32 v42, v42, v122
	v_sub_f32_e32 v43, v43, v122
	v_sub_f32_e32 v44, v44, v122
	v_sub_f32_e32 v45, v45, v122
	v_sub_f32_e32 v46, v46, v122
	v_sub_f32_e32 v47, v47, v122
	v_sub_f32_e32 v48, v48, v122
	v_sub_f32_e32 v49, v49, v122
	v_exp_f32_e64 v122, -v122
	s_nop 0
	v_mul_f32_e32 v2, v2, v122
	v_mul_f32_e32 v3, v3, v122
	v_mul_f32_e32 v4, v4, v122
	v_mul_f32_e32 v5, v5, v122
	v_mul_f32_e32 v6, v6, v122
	v_mul_f32_e32 v7, v7, v122
	v_mul_f32_e32 v8, v8, v122
	v_mul_f32_e32 v9, v9, v122
	v_mul_f32_e32 v10, v10, v122
	v_mul_f32_e32 v11, v11, v122
	v_mul_f32_e32 v12, v12, v122
	v_mul_f32_e32 v13, v13, v122
	v_mul_f32_e32 v14, v14, v122
	v_mul_f32_e32 v15, v15, v122
	v_mul_f32_e32 v16, v16, v122
	v_mul_f32_e32 v17, v17, v122
	v_mul_f32_e32 v18, v18, v122
	v_mul_f32_e32 v19, v19, v122
	v_mul_f32_e32 v20, v20, v122
	v_mul_f32_e32 v21, v21, v122
	v_mul_f32_e32 v22, v22, v122
	v_mul_f32_e32 v23, v23, v122
	v_mul_f32_e32 v24, v24, v122
	v_mul_f32_e32 v25, v25, v122
	v_mul_f32_e32 v26, v26, v122
	v_mul_f32_e32 v27, v27, v122
	v_mul_f32_e32 v28, v28, v122
	v_mul_f32_e32 v29, v29, v122
	v_mul_f32_e32 v30, v30, v122
	v_mul_f32_e32 v31, v31, v122
	v_mul_f32_e32 v32, v32, v122
	v_mul_f32_e32 v33, v33, v122
	v_mul_f32_e32 v135, v135, v122
	s_branch .Lm3_back_e
.Lm3_rare_o:
	s_nop 1
	v_cndmask_b32_e64 v122, 0, v120, vcc
	s_mov_b64 s[20:21], 0
	v_sub_f32_e32 v156, v156, v122
	v_sub_f32_e32 v157, v157, v122
	v_sub_f32_e32 v158, v158, v122
	v_sub_f32_e32 v159, v159, v122
	v_sub_f32_e32 v160, v160, v122
	v_sub_f32_e32 v161, v161, v122
	v_sub_f32_e32 v162, v162, v122
	v_sub_f32_e32 v163, v163, v122
	v_sub_f32_e32 v164, v164, v122
	v_sub_f32_e32 v165, v165, v122
	v_sub_f32_e32 v166, v166, v122
	v_sub_f32_e32 v167, v167, v122
	v_sub_f32_e32 v168, v168, v122
	v_sub_f32_e32 v169, v169, v122
	v_sub_f32_e32 v170, v170, v122
	v_sub_f32_e32 v171, v171, v122
	v_sub_f32_e32 v176, v176, v122
	v_sub_f32_e32 v177, v177, v122
	v_sub_f32_e32 v178, v178, v122
	v_sub_f32_e32 v179, v179, v122
	v_sub_f32_e32 v180, v180, v122
	v_sub_f32_e32 v181, v181, v122
	v_sub_f32_e32 v182, v182, v122
	v_sub_f32_e32 v183, v183, v122
	v_sub_f32_e32 v184, v184, v122
	v_sub_f32_e32 v185, v185, v122
	v_sub_f32_e32 v186, v186, v122
	v_sub_f32_e32 v187, v187, v122
	v_sub_f32_e32 v188, v188, v122
	v_sub_f32_e32 v189, v189, v122
	v_sub_f32_e32 v190, v190, v122
	v_sub_f32_e32 v191, v191, v122
	v_sub_f32_e32 v192, v192, v122
	v_sub_f32_e32 v193, v193, v122
	v_sub_f32_e32 v194, v194, v122
	v_sub_f32_e32 v195, v195, v122
	v_sub_f32_e32 v196, v196, v122
	v_sub_f32_e32 v197, v197, v122
	v_sub_f32_e32 v198, v198, v122
	v_sub_f32_e32 v199, v199, v122
	v_sub_f32_e32 v200, v200, v122
	v_sub_f32_e32 v201, v201, v122
	v_sub_f32_e32 v202, v202, v122
	v_sub_f32_e32 v203, v203, v122
	v_sub_f32_e32 v204, v204, v122
	v_sub_f32_e32 v205, v205, v122
	v_sub_f32_e32 v206, v206, v122
	v_sub_f32_e32 v207, v207, v122
	v_exp_f32_e64 v122, -v122
	s_nop 0
	v_mul_f32_e32 v2, v2, v122
	v_mul_f32_e32 v3, v3, v122
	v_mul_f32_e32 v4, v4, v122
	v_mul_f32_e32 v5, v5, v122
	v_mul_f32_e32 v6, v6, v122
	v_mul_f32_e32 v7, v7, v122
	v_mul_f32_e32 v8, v8, v122
	v_mul_f32_e32 v9, v9, v122
	v_mul_f32_e32 v10, v10, v122
	v_mul_f32_e32 v11, v11, v122
	v_mul_f32_e32 v12, v12, v122
	v_mul_f32_e32 v13, v13, v122
	v_mul_f32_e32 v14, v14, v122
	v_mul_f32_e32 v15, v15, v122
	v_mul_f32_e32 v16, v16, v122
	v_mul_f32_e32 v17, v17, v122
	v_mul_f32_e32 v18, v18, v122
	v_mul_f32_e32 v19, v19, v122
	v_mul_f32_e32 v20, v20, v122
	v_mul_f32_e32 v21, v21, v122
	v_mul_f32_e32 v22, v22, v122
	v_mul_f32_e32 v23, v23, v122
	v_mul_f32_e32 v24, v24, v122
	v_mul_f32_e32 v25, v25, v122
	v_mul_f32_e32 v26, v26, v122
	v_mul_f32_e32 v27, v27, v122
	v_mul_f32_e32 v28, v28, v122
	v_mul_f32_e32 v29, v29, v122
	v_mul_f32_e32 v30, v30, v122
	v_mul_f32_e32 v31, v31, v122
	v_mul_f32_e32 v32, v32, v122
	v_mul_f32_e32 v33, v33, v122
	v_mul_f32_e32 v135, v135, v122
	s_branch .Lm3_back_o

; DI unsigned pk2(float a, float b) { f32x2 v = {a, b}; return __builtin_bit_cast(unsigned, __builtin_convertvector(v, bf2_t)); }
; DI float bflo(unsigned u) { return __uint_as_float(u << 16); }
; DI float bfhi(unsigned u) { return __uint_as_float(u & 0xffff0000u); }
; DI float xhalf_other(float x, int h) { auto r = __builtin_amdgcn_permlane32_swap(__float_as_uint(x), __float_as_uint(x), false, false); return h ? __uint_as_float(r[0]) : __uint_as_float(r[1]); }
;     ...
;     if (MODE != 1) {
;         const float lt = lsum + xhalf_other(lsum, h), inv = __builtin_amdgcn_rcpf(lt);
;         o0 *= inv; o1 *= inv;
;     }
;     bf16_t* yrow = yb + (size_t)(32 * w + r) * 1024 + 4 * h;
;     const bf16_t* grow = gt + (size_t)(32 * w + r) * 1024 + 4 * h;
;     u32x2 gv[2][4];
; #pragma unroll
;     for (int nt = 0; nt < 2; ++nt)
; #pragma unroll
;         for (int qd = 0; qd < 4; ++qd) gv[nt][qd] = *(const u32x2*)(grow + 32 * nt + 8 * qd);
; #pragma unroll
;     for (int nt = 0; nt < 2; ++nt)
; #pragma unroll
;         for (int qd = 0; qd < 4; ++qd) {
;             const u32x2 g = gv[nt][qd];
;             const f32x16& o = nt ? o1 : o0;
;             u32x2 v;
;             v.x = pk2(o[4 * qd] * bflo(g.x), o[4 * qd + 1] * bfhi(g.x));
;             v.y = pk2(o[4 * qd + 2] * bflo(g.y), o[4 * qd + 3] * bfhi(g.y));
;             *(u32x2*)(yrow + 32 * nt + 8 * qd) = v;
;         }
.Lm3_exit:
.LBB0_785:
	s_mov_b32 s57, s49
	s_lshl_b64 s[4:5], s[94:95], 11
	s_lshl_b64 s[6:7], s[56:57], 24
	s_or_b64 s[4:5], s[4:5], s[6:7]
	s_add_u32 s6, s61, s4
	s_addc_u32 s7, s70, s5
	s_add_u32 s4, s69, s4
	v_mov_b32_e32 v0, v135
	v_mov_b32_e32 v34, v135
	s_addc_u32 s5, s60, s5
	s_lshl_b32 s8, s79, 7
	v_permlane32_swap_b32_e32 v0, v34
	v_cmp_eq_u32_e32 vcc, 0, v121
	s_add_u32 s4, s4, s8
	s_addc_u32 s5, s5, 0
	v_cndmask_b32_e32 v0, v0, v34, vcc
	v_add_f32_e32 v0, v135, v0
	v_lshlrev_b64 v[42:43], 11, v[110:111]
	v_rcp_f32_e32 v44, v0
	v_lshl_add_u64 v[34:35], s[4:5], 0, v[42:43]
	v_lshlrev_b32_e32 v0, 1, v123
	v_lshl_add_u64 v[34:35], v[34:35], 0, v[0:1]
	global_load_dwordx2 v[46:47], v[34:35], off
	global_load_dwordx2 v[48:49], v[34:35], off offset:16
	global_load_dwordx2 v[50:51], v[34:35], off offset:32
	global_load_dwordx2 v[52:53], v[34:35], off offset:48
	global_load_dwordx2 v[40:41], v[34:35], off offset:64
	global_load_dwordx2 v[38:39], v[34:35], off offset:80
	global_load_dwordx2 v[36:37], v[34:35], off offset:96
	s_nop 0
	global_load_dwordx2 v[34:35], v[34:35], off offset:112
	s_add_u32 s6, s6, s8
	s_addc_u32 s7, s7, 0
	v_pk_mul_f32 v[20:21], v[20:21], v[44:45] op_sel_hi:[1,0]
	v_pk_mul_f32 v[18:19], v[18:19], v[44:45] op_sel_hi:[1,0]
	v_lshl_add_u64 v[42:43], s[6:7], 0, v[42:43]
	v_lshl_add_u64 v[42:43], v[42:43], 0, v[0:1]
	v_pk_mul_f32 v[24:25], v[24:25], v[44:45] op_sel_hi:[1,0]
	v_pk_mul_f32 v[22:23], v[22:23], v[44:45] op_sel_hi:[1,0]
	v_pk_mul_f32 v[28:29], v[28:29], v[44:45] op_sel_hi:[1,0]
	v_pk_mul_f32 v[26:27], v[26:27], v[44:45] op_sel_hi:[1,0]
	v_pk_mul_f32 v[32:33], v[32:33], v[44:45] op_sel_hi:[1,0]
	v_pk_mul_f32 v[30:31], v[30:31], v[44:45] op_sel_hi:[1,0]
	v_pk_mul_f32 v[16:17], v[16:17], v[44:45] op_sel_hi:[1,0]
	v_pk_mul_f32 v[14:15], v[14:15], v[44:45] op_sel_hi:[1,0]
	v_pk_mul_f32 v[12:13], v[12:13], v[44:45] op_sel_hi:[1,0]
	v_pk_mul_f32 v[10:11], v[10:11], v[44:45] op_sel_hi:[1,0]
	v_pk_mul_f32 v[8:9], v[8:9], v[44:45] op_sel_hi:[1,0]
	v_pk_mul_f32 v[6:7], v[6:7], v[44:45] op_sel_hi:[1,0]
	v_pk_mul_f32 v[4:5], v[4:5], v[44:45] op_sel_hi:[1,0]
	v_pk_mul_f32 v[2:3], v[2:3], v[44:45] op_sel_hi:[1,0]
	s_mov_b32 s95, 0x7fffffe0
	s_waitcnt vmcnt(0) lgkmcnt(0)
	v_lshlrev_b32_e32 v54, 16, v46
	v_and_b32_e32 v55, 0xffff0000, v46
	v_lshlrev_b32_e32 v46, 16, v47
	v_and_b32_e32 v47, 0xffff0000, v47
	v_pk_mul_f32 v[18:19], v[18:19], v[54:55]
	v_pk_mul_f32 v[20:21], v[20:21], v[46:47]
	v_cvt_pk_bf16_f32 v18, v18, v19
	v_cvt_pk_bf16_f32 v19, v20, v21
	global_store_dwordx2 v[42:43], v[18:19], off
	v_lshlrev_b32_e32 v18, 16, v48
	v_and_b32_e32 v19, 0xffff0000, v48
	v_lshlrev_b32_e32 v20, 16, v49
	v_and_b32_e32 v21, 0xffff0000, v49
	v_pk_mul_f32 v[18:19], v[22:23], v[18:19]
	v_pk_mul_f32 v[20:21], v[24:25], v[20:21]
	v_cvt_pk_bf16_f32 v18, v18, v19
	v_cvt_pk_bf16_f32 v19, v20, v21
	global_store_dwordx2 v[42:43], v[18:19], off offset:16
	v_lshlrev_b32_e32 v18, 16, v50
	v_and_b32_e32 v19, 0xffff0000, v50
	v_lshlrev_b32_e32 v20, 16, v51
	v_and_b32_e32 v21, 0xffff0000, v51
	v_pk_mul_f32 v[18:19], v[26:27], v[18:19]
	v_pk_mul_f32 v[20:21], v[28:29], v[20:21]
	v_cvt_pk_bf16_f32 v18, v18, v19
	v_cvt_pk_bf16_f32 v19, v20, v21
	global_store_dwordx2 v[42:43], v[18:19], off offset:32
	v_lshlrev_b32_e32 v18, 16, v52
	v_and_b32_e32 v19, 0xffff0000, v52
	v_lshlrev_b32_e32 v20, 16, v53
	v_and_b32_e32 v21, 0xffff0000, v53
	v_pk_mul_f32 v[18:19], v[30:31], v[18:19]
	v_pk_mul_f32 v[20:21], v[32:33], v[20:21]
	v_cvt_pk_bf16_f32 v18, v18, v19
	v_cvt_pk_bf16_f32 v19, v20, v21
	global_store_dwordx2 v[42:43], v[18:19], off offset:48
